# P3: half the WGs run the elementwise GLA norm/gate pass first and their sample-row merge tiles last (v80 base)
# baseline (speedup 1.0000x reference)
; __global__ void __launch_bounds__(512, 2) hybrid_fwd(Args a) {
;     ...
;     if (IN(3)) {
;         for (int t = bx; t < 256; t += G) { SmMergeA E{Z, a.out, nullptr}; small_gemm_tile<SmMergeA>(lds, OCAT, OC, PCAT, OC, 1024, -1, MP, t >> 5, t & 31, E, tid); }
;         for (int t = bx; t < 256; t += G) { SmMergeB E{Z, a.out, Y, nullptr}; small_gemm_tile<SmMergeB>(lds, OCAT + 1024, OC, PCAT + 1024, OC, 2048, -1, MP, t >> 5, t & 31, E, tid); }
;         for (int it0 = gw; it0 < MP * 4; it0 += 4 * NGW) {
.LBB0_575:
	s_cmp_lt_i32 s90, 4
	s_cselect_b64 s[4:5], -1, 0
	s_and_b64 s[12:13], s[4:5], s[0:1]
	s_andn2_b64 vcc, exec, s[12:13]
	s_cbranch_vccnz .LBB0_593
	s_bfe_u32 s100, s2, 0x10003
	s_cmpk_gt_i32 s2, 0xff
	v_readlane_b32 s24, v249, 21
	v_readlane_b32 s25, v249, 22
	s_cbranch_scc1 .LBB0_581
	s_cmp_eq_u32 s100, 1
	s_cbranch_scc1 .LBB0_581
.Lp3_small:
	v_lshlrev_b32_e32 v1, 3, v188
	v_and_b32_e32 v10, 0xf8, v1
	v_readlane_b32 s0, v249, 23
	v_mov_b32_e32 v13, 0
	v_lshlrev_b32_e32 v12, 1, v10
	v_readlane_b32 s1, v249, 24
	v_lshrrev_b32_e32 v19, 1, v188
	v_and_b32_e32 v0, 15, v188
	v_lshl_add_u64 v[14:15], s[50:51], 0, v[12:13]
	v_lshl_add_u64 v[16:17], s[0:1], 0, v[12:13]
	v_add_u32_e32 v2, 0x200, v188
	v_add_u32_e32 v3, 0x600, v188
	v_bfe_u32 v11, v188, 4, 2
	v_lshlrev_b32_e32 v12, 4, v188
	v_lshrrev_b32_e32 v18, 3, v188
	s_movk_i32 s0, 0x70
	v_and_b32_e32 v19, 32, v19
	v_lshrrev_b32_e32 v1, 5, v188
	v_lshrrev_b32_e32 v2, 5, v2
	v_lshrrev_b32_e32 v3, 5, v3
	v_and_b32_e32 v12, 0x1f0, v12
	s_mov_b32 s9, 0
	v_and_or_b32 v36, v18, s0, v0
	v_lshl_add_u32 v18, v11, 4, 0
	s_movk_i32 s0, 0x210
	v_or_b32_e32 v0, v19, v0
	v_mul_u32_u24_e32 v4, 0x1800, v1
	v_mul_u32_u24_e32 v6, 0x1800, v2
	v_add_u32_e32 v12, 0, v12
	v_mad_u32_u24 v38, v0, s0, v18
	v_mul_u32_u24_e32 v0, 0x210, v1
	v_mul_u32_u24_e32 v1, 0x210, v2
	v_mul_u32_u24_e32 v2, 0x210, v3
	s_mov_b32 s8, s9
	v_mul_u32_u24_e32 v8, 0x1800, v3
	s_lshl_b32 s3, s2, 1
	v_add_u32_e32 v40, v12, v0
	v_add_u32_e32 v41, v12, v1
	v_add_u32_e32 v42, v12, v2
	s_mov_b32 s10, s9
	s_mov_b32 s11, s9
	v_mov_b64_e32 v[0:1], s[8:9]
	v_mov_b32_e32 v5, v13
	v_mov_b32_e32 v7, v13
	v_mov_b32_e32 v9, v13
	v_mad_u32_u24 v37, v36, s0, v18
	v_lshl_or_b32 v39, v11, 2, v19
	s_lshl_b32 s20, s24, 1
	v_mov_b32_e32 v11, 0x1800
	s_mov_b64 s[14:15], 0x30000
	s_mov_b32 s16, 0x30000
	v_mov_b64_e32 v[2:3], s[10:11]
	s_movk_i32 s17, 0x5e00
	v_mov_b64_e32 v[18:19], s[74:75]
	s_mov_b64 s[10:11], 0x3c00
	s_mov_b32 s18, s3
	s_mov_b32 s19, s2

; __global__ void __launch_bounds__(512, 2) hybrid_fwd(Args a) {
;     ...
;         for (int it0 = gw; it0 < MP * 4; it0 += 4 * NGW) {
;             u32x4 ow[4], rw[4]; float gp[4];
; #pragma unroll
;             for (int u = 0; u < 4; ++u) { const int it = it0 + u * NGW; const int row = it >> 2, h = it & 3;
;                 ow[u] = *(const u32x4*)(OCAT + (size_t)row * OC + 1024 + h * 512 + lane * 8); rw[u] = *(const u32x4*)(Z + (size_t)row * DINP + ZRG + h * 512 + lane * 8);
;                 gp[u] = lane < 32 ? GSS[(size_t)it * 32 + lane] : 0.f; }
;             const f32x4 g0 = *(const f32x4*)(a.gla_norm + lane * 8), g1 = *(const f32x4*)(a.gla_norm + lane * 8 + 4);
;             const float gn[8] = {g0[0], g0[1], g0[2], g0[3], g1[0], g1[1], g1[2], g1[3]};
; #pragma unroll
;             for (int u = 0; u < 4; ++u) { const int it = it0 + u * NGW; const int row = it >> 2, h = it & 3; const float rs = rsqrtf(wave_sum(gp[u]) * (1.0f / 512.0f) + EPS);
.LBB0_581:
	s_cmp_eq_u32 s100, 2
	s_cbranch_scc1 .LBB0_593
	s_mov_b32 s0, 0x10000
	v_cmp_gt_i32_e32 vcc, s0, v184
	s_and_saveexec_b64 s[8:9], vcc
	s_cbranch_execz .LBB0_592
	v_mbcnt_lo_u32_b32 v1, -1, 0
	v_mbcnt_hi_u32_b32 v1, -1, v1
	v_and_b32_e32 v2, 64, v1
	v_add_u32_e32 v2, 64, v2
	v_xor_b32_e32 v3, 1, v1
	v_cmp_lt_i32_e32 vcc, v3, v2
	v_lshlrev_b32_e32 v0, 3, v186
	v_mov_b32_e32 v41, 0
	v_cndmask_b32_e32 v3, v1, v3, vcc
	v_lshlrev_b32_e32 v62, 2, v3
	v_xor_b32_e32 v3, 2, v1
	v_cmp_lt_i32_e32 vcc, v3, v2
	v_lshlrev_b32_e32 v40, 2, v186
	v_readlane_b32 s16, v249, 5
	v_cndmask_b32_e32 v3, v1, v3, vcc
	v_lshlrev_b32_e32 v63, 2, v3
	v_xor_b32_e32 v3, 4, v1
	v_cmp_lt_i32_e32 vcc, v3, v2
	v_lshl_add_u64 v[42:43], s[48:49], 0, v[40:41]
	v_lshlrev_b32_e32 v40, 5, v186
	v_cndmask_b32_e32 v3, v1, v3, vcc
	v_lshlrev_b32_e32 v64, 2, v3
	v_xor_b32_e32 v3, 8, v1
	v_cmp_lt_i32_e32 vcc, v3, v2
	v_readlane_b32 s17, v249, 6
	v_readlane_b32 s18, v249, 7
	v_cndmask_b32_e32 v3, v1, v3, vcc
	v_lshlrev_b32_e32 v65, 2, v3
	v_xor_b32_e32 v3, 16, v1
	v_cmp_lt_i32_e32 vcc, v3, v2
	v_readlane_b32 s19, v249, 8
	v_readlane_b32 s20, v249, 9
	v_cndmask_b32_e32 v3, v1, v3, vcc
	v_lshlrev_b32_e32 v66, 2, v3
	v_xor_b32_e32 v3, 32, v1
	v_cmp_lt_i32_e32 vcc, v3, v2
	v_readlane_b32 s21, v249, 10
	v_readlane_b32 s0, v249, 21
	v_cndmask_b32_e32 v1, v1, v3, vcc
	v_lshlrev_b32_e32 v67, 2, v1
	v_lshlrev_b32_e32 v1, 9, v148
	v_lshlrev_b32_e32 v48, 1, v0
	v_cmp_gt_u32_e64 s[4:5], 32, v186
	v_lshl_add_u64 v[44:45], s[20:21], 0, v[40:41]
	s_lshl_b32 s3, s0, 4
	s_mul_i32 s14, s0, 24
	v_lshl_add_u32 v68, s2, 12, v1
	s_lshl_b32 s15, s0, 14
	s_mov_b64 s[10:11], 0
	s_movk_i32 s16, 0x1800
	v_mov_b64_e32 v[46:47], s[50:51]
	v_mov_b32_e32 v50, v48
	v_mov_b32_e32 v51, v41
	s_movk_i32 s17, 0x5e00
	v_mov_b64_e32 v[52:53], s[74:75]
	v_mov_b32_e32 v69, 0x358637bd
	s_mov_b32 s18, 0x800000
	s_mov_b32 s19, 0xffff
	v_mov_b32_e32 v0, v184
	v_readlane_b32 s22, v249, 11
	v_readlane_b32 s23, v249, 12
	v_readlane_b32 s24, v249, 13
	v_readlane_b32 s25, v249, 14
	v_readlane_b32 s26, v249, 15
	v_readlane_b32 s27, v249, 16
	v_readlane_b32 s28, v249, 17
	v_readlane_b32 s29, v249, 18
	v_readlane_b32 s30, v249, 19
	v_readlane_b32 s31, v249, 20
	v_readlane_b32 s1, v249, 22
	s_branch .LBB0_584

; __global__ void __launch_bounds__(512, 2) hybrid_fwd(Args a) {
;     ...
;         for (int t = bx; t < 256; t += G) { SmMergeA E{Z, a.out, nullptr}; small_gemm_tile<SmMergeA>(lds, OCAT, OC, PCAT, OC, 1024, -1, MP, t >> 5, t & 31, E, tid); }
;         for (int t = bx; t < 256; t += G) { SmMergeB E{Z, a.out, Y, nullptr}; small_gemm_tile<SmMergeB>(lds, OCAT + 1024, OC, PCAT + 1024, OC, 2048, -1, MP, t >> 5, t & 31, E, tid); }
;         for (int it0 = gw; it0 < MP * 4; it0 += 4 * NGW) {
.LBB0_592:
	s_or_b64 exec, exec, s[8:9]
	s_cmp_eq_u32 s100, 1
	s_cbranch_scc0 .LBB0_593
	s_mov_b32 s100, 2
	v_readlane_b32 s24, v249, 21
	v_readlane_b32 s25, v249, 22
	s_branch .Lp3_small
